# v63 + P10 queue order: the 12 HBM-bound late weight-conversion items interleaved with the VALU-bound top-k rows (queue slots 5,8,..,38) instead of all at the end of the queue
# baseline (speedup 1.0000x reference)
; #define LAS __attribute__((address_space(3)))
; __global__ void __launch_bounds__(NTHR, 2) mk_fwd(Args args) {
;     ...
;         for (;;) {
;             int it = 0;
;             if (lane == 0) it = __hip_atomic_fetch_add((LAS int*)(lds + MISC_OFF) + 12, 1, __ATOMIC_RELAXED, __HIP_MEMORY_SCOPE_WORKGROUP);
;             it = __builtin_amdgcn_readfirstlane(it);
;             if (it >= 34 + 12) break;
;             if (it >= 34) { const int L = bid + G * (it - 34); if (L < LATE_N) LATE_TR(L); continue; }
.LBB0_1602:
	s_or_b64 exec, exec, s[14:15]
	v_readfirstlane_b32 s72, v0
	s_cmp_gt_i32 s72, 45
	s_mov_b64 s[14:15], -1
	s_cbranch_scc1 .LBB0_1597
	s_cmp_lt_i32 s72, 2
	s_cbranch_scc1 .Lmy_q_done
	s_mov_b32 s100, 0x24924920
	s_mov_b32 s101, 0x49
	s_bitcmp1_b64 s[100:101], s72
	s_cselect_b32 s32, 1, 0
	s_sub_i32 s6, 64, s72
	s_lshl_b64 s[100:101], s[100:101], s6
	s_bcnt1_i32_b64 s6, s[100:101]
	s_sub_i32 s100, s72, s6
	s_add_i32 s101, s6, 34
	s_cmp_lg_u32 s32, 0
	s_cselect_b32 s72, s101, s100
.Lmy_q_done:
	s_cmp_lt_i32 s72, 34
	s_cbranch_scc1 .LBB0_1604
	s_getpc_b64 s[98:99]
